# phase 0 row-norm wave sum: permlane32/16 swap + DPP row_ror adds instead of six LDS bpermute round trips (same summation tree)
# baseline (speedup 1.0000x reference)
; __device__ __forceinline__ unsigned cvtpk(float lo, float hi) { f32x2_t v = {lo, hi}; bf16x2_t b = __builtin_convertvector(v, bf16x2_t); return __builtin_bit_cast(unsigned, b); }
; __device__ __forceinline__ float wave_sum(float v) {
; #pragma unroll
;   for (int o = 32; o > 0; o >>= 1) v += __shfl_xor(v, o);
;   return v;
; }
; __device__ __forceinline__ void phase0(const Params& p, unsigned char* smem) {
;     ...
;       int row = it * 4 + wave; int b = row / LTOK, pos = row - b * LTOK;
;       const float* src = pos < NMETA ? p.meta + pos * DM : p.x + ((size_t)b * SEQ + pos - NMETA) * DM;
;       float4 v[4]; float ss = 0.f;
; #pragma unroll
;       for (int i = 0; i < 4; ++i) { v[i] = ((const float4*)src)[lane + 64 * i]; ss += v[i].x * v[i].x + v[i].y * v[i].y + v[i].z * v[i].z + v[i].w * v[i].w; }
;       ss = wave_sum(ss);
;       float rs = rsqrtf(ss * (1.f / 1024.f) + 1e-6f);
; #pragma unroll
;       for (int i = 0; i < 4; ++i) {
;         float4 w = ((const float4*)p.norm_w)[lane + 64 * i];
;         uint2 o; o.x = cvtpk(v[i].x * rs * w.x, v[i].y * rs * w.y); o.y = cvtpk(v[i].z * rs * w.z, v[i].w * rs * w.w);
;         ((uint2*)(hn + (size_t)row * DM))[lane + 64 * i] = o;
;       }
.LBB0_2:
	s_or_b64 exec, exec, s[10:11]
	v_mov_b32_e32 v23, v7
	v_lshl_add_u64 v[30:31], v[28:29], 0, v[22:23]
	global_load_dwordx4 v[26:29], v[30:31], off
	global_load_dwordx4 v[52:55], v[30:31], off offset:1024
	global_load_dwordx4 v[56:59], v[30:31], off offset:2048
	global_load_dwordx4 v[60:63], v[30:31], off offset:3072
	s_waitcnt vmcnt(3)
	v_mov_b32_e32 v72, v27
	s_waitcnt vmcnt(2)
	v_mov_b32_e32 v73, v53
	v_mov_b32_e32 v70, v26
	v_mov_b32_e32 v71, v52
	s_waitcnt vmcnt(1)
	v_mov_b32_e32 v80, v57
	s_waitcnt vmcnt(0)
	v_mov_b32_e32 v81, v61
	v_pk_mul_f32 v[72:73], v[72:73], v[72:73]
	v_mov_b32_e32 v30, v28
	v_mov_b32_e32 v31, v54
	v_mov_b32_e32 v78, v56
	v_mov_b32_e32 v79, v60
	v_pk_mul_f32 v[80:81], v[80:81], v[80:81]
	v_pk_fma_f32 v[70:71], v[70:71], v[70:71], v[72:73]
	v_mov_b32_e32 v68, v29
	v_mov_b32_e32 v69, v55
	v_mov_b32_e32 v74, v58
	v_mov_b32_e32 v75, v62
	v_pk_fma_f32 v[72:73], v[78:79], v[78:79], v[80:81]
	v_pk_fma_f32 v[30:31], v[30:31], v[30:31], v[70:71]
	v_mov_b32_e32 v76, v59
	v_mov_b32_e32 v77, v63
	v_pk_fma_f32 v[70:71], v[74:75], v[74:75], v[72:73]
	v_pk_fma_f32 v[30:31], v[68:69], v[68:69], v[30:31]
	v_pk_fma_f32 v[68:69], v[76:77], v[76:77], v[70:71]
	v_add_f32_e32 v30, v30, v31
	v_add_f32_e32 v30, v30, v68
	v_add_f32_e32 v30, v30, v69
	v_mov_b32_e32 v25, v30
	s_nop 1
	v_permlane32_swap_b32_e32 v30, v25
	s_nop 1
	v_add_f32_e32 v30, v30, v25
	v_mov_b32_e32 v25, v30
	s_nop 1
	v_permlane16_swap_b32_e32 v30, v25
	s_nop 1
	v_add_f32_e32 v30, v30, v25
	s_nop 1
	v_add_f32_dpp v25, v30, v30 row_ror:8 row_mask:0xf bank_mask:0xf
	s_nop 1
	v_add_f32_dpp v30, v25, v25 row_ror:4 row_mask:0xf bank_mask:0xf
	s_nop 1
	v_add_f32_dpp v25, v30, v30 row_ror:2 row_mask:0xf bank_mask:0xf
	s_nop 1
	v_add_f32_dpp v23, v25, v25 row_ror:1 row_mask:0xf bank_mask:0xf
	v_fmamk_f32 v23, v23, 0x3a800000, v47
	v_mul_f32_e32 v25, 0x4b800000, v23
	v_cmp_gt_f32_e32 vcc, s58, v23
	s_nop 1
	v_cndmask_b32_e32 v23, v23, v25, vcc
	v_rsq_f32_e32 v23, v23
	v_ashrrev_i32_e32 v25, 31, v24
	v_lshlrev_b64 v[24:25], 11, v[24:25]
	v_lshl_add_u64 v[30:31], v[20:21], 0, v[24:25]
	v_mul_f32_e32 v24, 0x45800000, v23
	v_cndmask_b32_e32 v68, v23, v24, vcc
	v_pk_mul_f32 v[24:25], v[26:27], v[68:69] op_sel_hi:[1,0]
	v_pk_mul_f32 v[26:27], v[28:29], v[68:69] op_sel_hi:[1,0]
	v_pk_mul_f32 v[24:25], v[100:101], v[24:25]
	v_pk_mul_f32 v[26:27], v[102:103], v[26:27]
	v_cvt_pk_bf16_f32 v24, v24, v25
	v_cvt_pk_bf16_f32 v25, v26, v27
	global_store_dwordx2 v[30:31], v[24:25], off sc1
	v_pk_mul_f32 v[28:29], v[52:53], v[68:69] op_sel_hi:[1,0]
	v_pk_mul_f32 v[52:53], v[54:55], v[68:69] op_sel_hi:[1,0]
	v_pk_mul_f32 v[24:25], v[104:105], v[28:29]
	v_pk_mul_f32 v[26:27], v[106:107], v[52:53]
	v_cvt_pk_bf16_f32 v24, v24, v25
	v_cvt_pk_bf16_f32 v25, v26, v27
	global_store_dwordx2 v[30:31], v[24:25], off offset:512 sc1
	v_pk_mul_f32 v[28:29], v[56:57], v[68:69] op_sel_hi:[1,0]
	v_pk_mul_f32 v[52:53], v[58:59], v[68:69] op_sel_hi:[1,0]
	v_pk_mul_f32 v[24:25], v[28:29], v[108:109]
	v_pk_mul_f32 v[26:27], v[52:53], v[110:111]
	v_cvt_pk_bf16_f32 v24, v24, v25
	v_cvt_pk_bf16_f32 v25, v26, v27
	global_store_dwordx2 v[30:31], v[24:25], off offset:1024 sc1
	v_pk_mul_f32 v[28:29], v[60:61], v[68:69] op_sel_hi:[1,0]
	v_pk_mul_f32 v[52:53], v[62:63], v[68:69] op_sel_hi:[1,0]
	v_pk_mul_f32 v[24:25], v[28:29], v[112:113]
	v_pk_mul_f32 v[26:27], v[52:53], v[114:115]
	v_cvt_pk_bf16_f32 v24, v24, v25
	v_cvt_pk_bf16_f32 v25, v26, v27
	global_store_dwordx2 v[30:31], v[24:25], off offset:1536 sc1
